# accumulator zeroing per unit with 64-bit v_mov_b64 (63 instead of 126 moves, 5 GEMM unit loops)
# speedup vs baseline: 1.0198x; 1.0047x over previous
.LBB0_65:
	s_ashr_i32 s31, s30, 31
	s_nop 1
	s_lshl_b64 s[26:27], s[30:31], 19
	v_readlane_b32 s6, v253, 18
	v_readlane_b32 s7, v253, 19
	s_add_u32 s34, s6, s26
	s_addc_u32 s35, s7, s27
	s_cmp_eq_u32 s101, 2
	s_cselect_b32 s26, 0x40000, 0
	s_add_u32 s34, s34, s26
	s_addc_u32 s35, s35, 0
	s_and_b64 s[26:27], s[44:45], exec
	s_cselect_b32 s31, s35, s41
	s_cselect_b32 s80, s34, s40
	s_ashr_i32 s29, s28, 31
	s_lshl_b64 s[26:27], s[28:29], 19
	s_add_u32 s36, s48, s26
	s_addc_u32 s37, s49, s27
	s_and_b64 s[26:27], s[44:45], exec
	s_cselect_b32 s29, s37, s43
	s_cselect_b32 vcc_lo, s36, s42
	s_add_u32 s40, s40, 0x40080
	s_addc_u32 s41, s41, 0
	s_add_u32 s26, s42, 0x100
	v_mov_b32_e32 v0, 0
	s_addc_u32 s27, s43, 0
	s_mov_b32 s96, -2
	v_mov_b32_e32 v1, v0
	v_mov_b64_e32 v[2:3], 0
	v_mov_b64_e32 v[8:9], 0
	v_mov_b64_e32 v[10:11], 0
	v_mov_b64_e32 v[16:17], 0
	v_mov_b64_e32 v[18:19], 0
	v_mov_b64_e32 v[24:25], 0
	v_mov_b64_e32 v[26:27], 0
	v_mov_b64_e32 v[32:33], 0
	v_mov_b64_e32 v[34:35], 0
	v_mov_b64_e32 v[40:41], 0
	v_mov_b64_e32 v[42:43], 0
	v_mov_b64_e32 v[48:49], 0
	v_mov_b64_e32 v[50:51], 0
	v_mov_b64_e32 v[56:57], 0
	v_mov_b64_e32 v[58:59], 0
	v_mov_b64_e32 v[4:5], 0
	v_mov_b64_e32 v[6:7], 0
	v_mov_b64_e32 v[12:13], 0
	v_mov_b64_e32 v[14:15], 0
	v_mov_b64_e32 v[20:21], 0
	v_mov_b64_e32 v[22:23], 0
	v_mov_b64_e32 v[28:29], 0
	v_mov_b64_e32 v[30:31], 0
	v_mov_b64_e32 v[36:37], 0
	v_mov_b64_e32 v[38:39], 0
	v_mov_b64_e32 v[44:45], 0
	v_mov_b64_e32 v[46:47], 0
	v_mov_b64_e32 v[52:53], 0
	v_mov_b64_e32 v[54:55], 0
	v_mov_b64_e32 v[60:61], 0
	v_mov_b64_e32 v[62:63], 0
	v_mov_b64_e32 v[64:65], 0
	v_mov_b64_e32 v[66:67], 0
	v_mov_b64_e32 v[72:73], 0
	v_mov_b64_e32 v[74:75], 0
	v_mov_b64_e32 v[80:81], 0
	v_mov_b64_e32 v[82:83], 0
	v_mov_b64_e32 v[88:89], 0
	v_mov_b64_e32 v[90:91], 0
	v_mov_b64_e32 v[96:97], 0
	v_mov_b64_e32 v[98:99], 0
	v_mov_b64_e32 v[104:105], 0
	v_mov_b64_e32 v[106:107], 0
	v_mov_b64_e32 v[112:113], 0
	v_mov_b64_e32 v[114:115], 0
	v_mov_b64_e32 v[120:121], 0
	v_mov_b64_e32 v[122:123], 0
	v_mov_b64_e32 v[68:69], 0
	v_mov_b64_e32 v[70:71], 0
	v_mov_b64_e32 v[76:77], 0
	v_mov_b64_e32 v[78:79], 0
	v_mov_b64_e32 v[84:85], 0
	v_mov_b64_e32 v[86:87], 0
	v_mov_b64_e32 v[92:93], 0
	v_mov_b64_e32 v[94:95], 0
	v_mov_b64_e32 v[100:101], 0
	v_mov_b64_e32 v[102:103], 0
	v_mov_b64_e32 v[108:109], 0
	v_mov_b64_e32 v[110:111], 0
	v_mov_b64_e32 v[116:117], 0
	v_mov_b64_e32 v[118:119], 0
	v_mov_b64_e32 v[124:125], 0
	v_mov_b64_e32 v[126:127], 0
	s_nop 1
	v_add_u32_e32 v230, 0x10000, v140

.LBB0_93:
	s_add_u32 s30, s30, 0x80
	s_addc_u32 s31, s31, 0
	s_add_u32 s26, s34, 0x100
	v_mov_b32_e32 v0, 0
	s_addc_u32 s27, s35, 0
	s_mov_b32 s34, 0
	v_mov_b32_e32 v1, v0
	v_mov_b64_e32 v[2:3], 0
	v_mov_b64_e32 v[4:5], 0
	v_mov_b64_e32 v[6:7], 0
	v_mov_b64_e32 v[8:9], 0
	v_mov_b64_e32 v[10:11], 0
	v_mov_b64_e32 v[12:13], 0
	v_mov_b64_e32 v[14:15], 0
	v_mov_b64_e32 v[16:17], 0
	v_mov_b64_e32 v[18:19], 0
	v_mov_b64_e32 v[20:21], 0
	v_mov_b64_e32 v[22:23], 0
	v_mov_b64_e32 v[24:25], 0
	v_mov_b64_e32 v[26:27], 0
	v_mov_b64_e32 v[28:29], 0
	v_mov_b64_e32 v[30:31], 0
	v_mov_b64_e32 v[32:33], 0
	v_mov_b64_e32 v[34:35], 0
	v_mov_b64_e32 v[36:37], 0
	v_mov_b64_e32 v[38:39], 0
	v_mov_b64_e32 v[40:41], 0
	v_mov_b64_e32 v[42:43], 0
	v_mov_b64_e32 v[44:45], 0
	v_mov_b64_e32 v[46:47], 0
	v_mov_b64_e32 v[48:49], 0
	v_mov_b64_e32 v[50:51], 0
	v_mov_b64_e32 v[52:53], 0
	v_mov_b64_e32 v[54:55], 0
	v_mov_b64_e32 v[56:57], 0
	v_mov_b64_e32 v[58:59], 0
	v_mov_b64_e32 v[60:61], 0
	v_mov_b64_e32 v[62:63], 0
	v_mov_b64_e32 v[64:65], 0
	v_mov_b64_e32 v[66:67], 0
	v_mov_b64_e32 v[68:69], 0
	v_mov_b64_e32 v[70:71], 0
	v_mov_b64_e32 v[72:73], 0
	v_mov_b64_e32 v[74:75], 0
	v_mov_b64_e32 v[76:77], 0
	v_mov_b64_e32 v[78:79], 0
	v_mov_b64_e32 v[80:81], 0
	v_mov_b64_e32 v[82:83], 0
	v_mov_b64_e32 v[84:85], 0
	v_mov_b64_e32 v[86:87], 0
	v_mov_b64_e32 v[88:89], 0
	v_mov_b64_e32 v[90:91], 0
	v_mov_b64_e32 v[92:93], 0
	v_mov_b64_e32 v[94:95], 0
	v_mov_b64_e32 v[96:97], 0
	v_mov_b64_e32 v[98:99], 0
	v_mov_b64_e32 v[100:101], 0
	v_mov_b64_e32 v[102:103], 0
	v_mov_b64_e32 v[104:105], 0
	v_mov_b64_e32 v[106:107], 0
	v_mov_b64_e32 v[108:109], 0
	v_mov_b64_e32 v[110:111], 0
	v_mov_b64_e32 v[112:113], 0
	v_mov_b64_e32 v[114:115], 0
	v_mov_b64_e32 v[116:117], 0
	v_mov_b64_e32 v[118:119], 0
	v_mov_b64_e32 v[120:121], 0
	v_mov_b64_e32 v[122:123], 0
	v_mov_b64_e32 v[124:125], 0
	v_mov_b64_e32 v[126:127], 0
	s_cmp_lg_u32 s100, 0
	s_cselect_b64 vcc, -1, 0
	v_add_u32_e32 v251, 0x10000, v142

.LBB0_233:
	s_add_i32 s62, s62, 1
	s_waitcnt lgkmcnt(0)
	s_mul_i32 s0, s62, s90
	s_mov_b64 s[26:27], s[22:23]
	s_add_i32 s22, s0, s96
	s_cmpk_lt_i32 s22, 0x100
	s_cselect_b64 s[30:31], -1, 0
	s_cmpk_gt_i32 s22, 0xff
	s_mov_b64 s[34:35], s[28:29]
	s_mov_b32 s20, s69
	s_mov_b32 s29, s68
	s_mov_b32 s28, s65
	s_cselect_b64 s[0:1], -1, 0
	s_and_b32 s68, s22, 3
	s_bfe_u32 s69, s22, 0x30002
	s_ashr_i32 s65, s22, 5
	s_and_b64 s[22:23], s[30:31], exec
	s_cselect_b32 s29, s68, s29
	s_cselect_b32 s28, s65, s28
	s_cselect_b32 s22, s69, s20
	s_lshl_b32 s36, s29, 10
	s_ashr_i32 s23, s22, 31
	s_ashr_i32 s37, s36, 31
	s_nop 1
	s_lshl_b64 s[22:23], s[22:23], 21
	s_lshl_b64 s[36:37], s[36:37], 1
	v_readlane_b32 s16, v253, 12
	v_readlane_b32 s17, v253, 13
	s_add_u32 s20, s16, s22
	s_addc_u32 s23, s17, s23
	s_add_u32 s22, s20, s36
	s_addc_u32 s23, s23, s37
	s_and_b64 vcc, s[30:31], exec
	s_cselect_b32 vcc_lo, s23, s27
	s_cselect_b32 vcc_hi, s22, s26
	s_ashr_i32 s29, s28, 31
	s_lshl_b64 s[28:29], s[28:29], 13
	s_add_u32 s20, s78, s28
	s_addc_u32 s29, s79, s29
	s_add_u32 s28, s20, s36
	s_addc_u32 s29, s29, s37
	s_and_b64 s[30:31], s[30:31], exec
	s_cselect_b32 s33, s29, s35
	s_cselect_b32 s20, s28, s34
	s_add_u32 s30, s26, 0x100080
	s_addc_u32 s31, s27, 0
	s_add_u32 s26, s34, 0x100
	v_mov_b32_e32 v0, 0
	s_addc_u32 s27, s35, 0
	s_mov_b32 s96, -2
	v_mov_b32_e32 v1, v0
	v_mov_b64_e32 v[2:3], 0
	v_mov_b64_e32 v[4:5], 0
	v_mov_b64_e32 v[6:7], 0
	v_mov_b64_e32 v[8:9], 0
	v_mov_b64_e32 v[10:11], 0
	v_mov_b64_e32 v[12:13], 0
	v_mov_b64_e32 v[14:15], 0
	v_mov_b64_e32 v[16:17], 0
	v_mov_b64_e32 v[18:19], 0
	v_mov_b64_e32 v[20:21], 0
	v_mov_b64_e32 v[22:23], 0
	v_mov_b64_e32 v[24:25], 0
	v_mov_b64_e32 v[26:27], 0
	v_mov_b64_e32 v[28:29], 0
	v_mov_b64_e32 v[30:31], 0
	v_mov_b64_e32 v[32:33], 0
	v_mov_b64_e32 v[34:35], 0
	v_mov_b64_e32 v[36:37], 0
	v_mov_b64_e32 v[38:39], 0
	v_mov_b64_e32 v[40:41], 0
	v_mov_b64_e32 v[42:43], 0
	v_mov_b64_e32 v[44:45], 0
	v_mov_b64_e32 v[46:47], 0
	v_mov_b64_e32 v[48:49], 0
	v_mov_b64_e32 v[50:51], 0
	v_mov_b64_e32 v[52:53], 0
	v_mov_b64_e32 v[54:55], 0
	v_mov_b64_e32 v[56:57], 0
	v_mov_b64_e32 v[58:59], 0
	v_mov_b64_e32 v[60:61], 0
	v_mov_b64_e32 v[62:63], 0
	v_mov_b64_e32 v[64:65], 0
	v_mov_b64_e32 v[66:67], 0
	v_mov_b64_e32 v[68:69], 0
	v_mov_b64_e32 v[70:71], 0
	v_mov_b64_e32 v[72:73], 0
	v_mov_b64_e32 v[74:75], 0
	v_mov_b64_e32 v[76:77], 0
	v_mov_b64_e32 v[78:79], 0
	v_mov_b64_e32 v[80:81], 0
	v_mov_b64_e32 v[82:83], 0
	v_mov_b64_e32 v[84:85], 0
	v_mov_b64_e32 v[86:87], 0
	v_mov_b64_e32 v[88:89], 0
	v_mov_b64_e32 v[90:91], 0
	v_mov_b64_e32 v[92:93], 0
	v_mov_b64_e32 v[94:95], 0
	v_mov_b64_e32 v[96:97], 0
	v_mov_b64_e32 v[98:99], 0
	v_mov_b64_e32 v[100:101], 0
	v_mov_b64_e32 v[102:103], 0
	v_mov_b64_e32 v[104:105], 0
	v_mov_b64_e32 v[106:107], 0
	v_mov_b64_e32 v[108:109], 0
	v_mov_b64_e32 v[110:111], 0
	v_mov_b64_e32 v[112:113], 0
	v_mov_b64_e32 v[114:115], 0
	v_mov_b64_e32 v[116:117], 0
	v_mov_b64_e32 v[118:119], 0
	v_mov_b64_e32 v[120:121], 0
	v_mov_b64_e32 v[122:123], 0
	v_mov_b64_e32 v[124:125], 0
	v_mov_b64_e32 v[126:127], 0
	s_nop 1
	v_add_u32_e32 v230, 0x10000, v143

.LBB0_244:
	s_add_i32 s55, s55, 1
	s_mov_b64 s[26:27], s[22:23]
	s_mul_i32 s22, s55, s90
	s_mov_b32 s20, s58
	s_add_i32 s58, s22, s0
	s_cmp_lt_i32 s58, 8
	s_cselect_b32 s22, s58, s20
	s_ashr_i32 s23, s22, 31
	s_nop 1
	s_lshl_b64 s[22:23], s[22:23], 10
	v_readlane_b32 s12, v253, 24
	v_readlane_b32 s13, v253, 25
	s_add_u32 s22, s12, s22
	s_addc_u32 s23, s13, s23
	s_cmp_lt_i32 s58, 8
	s_cselect_b32 s20, s23, s27
	s_cselect_b32 s60, s22, s26
	s_cmp_gt_i32 s58, 7
	s_cselect_b64 s[28:29], -1, 0
	s_add_u32 s26, s26, 0x100
	v_mov_b32_e32 v0, 0
	v_readlane_b32 s30, v255, 17
	s_nop 1
	s_addc_u32 s27, s27, 0
	s_mov_b32 s61, -2
	v_readlane_b32 s31, v255, 18
	v_mov_b32_e32 v1, v0
	v_mov_b64_e32 v[2:3], 0
	v_mov_b64_e32 v[4:5], 0
	v_mov_b64_e32 v[6:7], 0
	v_mov_b64_e32 v[8:9], 0
	v_mov_b64_e32 v[10:11], 0
	v_mov_b64_e32 v[12:13], 0
	v_mov_b64_e32 v[14:15], 0
	v_mov_b64_e32 v[16:17], 0
	v_mov_b64_e32 v[18:19], 0
	v_mov_b64_e32 v[20:21], 0
	v_mov_b64_e32 v[22:23], 0
	v_mov_b64_e32 v[24:25], 0
	v_mov_b64_e32 v[26:27], 0
	v_mov_b64_e32 v[28:29], 0
	v_mov_b64_e32 v[30:31], 0
	v_mov_b64_e32 v[32:33], 0
	v_mov_b64_e32 v[34:35], 0
	v_mov_b64_e32 v[36:37], 0
	v_mov_b64_e32 v[38:39], 0
	v_mov_b64_e32 v[40:41], 0
	v_mov_b64_e32 v[42:43], 0
	v_mov_b64_e32 v[44:45], 0
	v_mov_b64_e32 v[46:47], 0
	v_mov_b64_e32 v[48:49], 0
	v_mov_b64_e32 v[50:51], 0
	v_mov_b64_e32 v[52:53], 0
	v_mov_b64_e32 v[54:55], 0
	v_mov_b64_e32 v[56:57], 0
	v_mov_b64_e32 v[58:59], 0
	v_mov_b64_e32 v[60:61], 0
	v_mov_b64_e32 v[62:63], 0
	v_mov_b64_e32 v[64:65], 0
	v_mov_b64_e32 v[66:67], 0
	v_mov_b64_e32 v[68:69], 0
	v_mov_b64_e32 v[70:71], 0
	v_mov_b64_e32 v[72:73], 0
	v_mov_b64_e32 v[74:75], 0
	v_mov_b64_e32 v[76:77], 0
	v_mov_b64_e32 v[78:79], 0
	v_mov_b64_e32 v[80:81], 0
	v_mov_b64_e32 v[82:83], 0
	v_mov_b64_e32 v[84:85], 0
	v_mov_b64_e32 v[86:87], 0
	v_mov_b64_e32 v[88:89], 0
	v_mov_b64_e32 v[90:91], 0
	v_mov_b64_e32 v[92:93], 0
	v_mov_b64_e32 v[94:95], 0
	v_mov_b64_e32 v[96:97], 0
	v_mov_b64_e32 v[98:99], 0
	v_mov_b64_e32 v[100:101], 0
	v_mov_b64_e32 v[102:103], 0
	v_mov_b64_e32 v[104:105], 0
	v_mov_b64_e32 v[106:107], 0
	v_mov_b64_e32 v[108:109], 0
	v_mov_b64_e32 v[110:111], 0
	v_mov_b64_e32 v[112:113], 0
	v_mov_b64_e32 v[114:115], 0
	v_mov_b64_e32 v[116:117], 0
	v_mov_b64_e32 v[118:119], 0
	v_mov_b64_e32 v[120:121], 0
	v_mov_b64_e32 v[122:123], 0
	v_mov_b64_e32 v[124:125], 0
	v_mov_b64_e32 v[126:127], 0
	v_readlane_b32 s78, v253, 14
	v_readlane_b32 s79, v253, 15
	s_nop 1
	v_readlane_b32 s65, v253, 1
	s_nop 1
	v_readlane_b32 s68, v253, 4
	v_readlane_b32 s69, v253, 5
	s_nop 1
	v_add_u32_e32 v230, 0x10000, v143

.LBB0_298:
	s_lshl_b32 s20, s55, 8
	s_addk_i32 s20, 0x1800
	s_cmp_eq_u32 s54, 0
	s_nop 1
	s_cselect_b32 s26, s55, s20
	v_readlane_b32 s6, v253, 18
	v_readlane_b32 s7, v253, 19
	s_cselect_b32 s20, 19, 11
	s_cselect_b32 s34, s7, s57
	s_cselect_b32 s35, s6, s56
	s_cselect_b32 s36, s56, s6
	s_cselect_b32 s37, s57, s7
	s_ashr_i32 s27, s26, 31
	s_lshl_b64 s[26:27], s[26:27], s20
	s_add_u32 s42, s35, s26
	s_addc_u32 s43, s34, s27
	s_and_b64 s[26:27], s[30:31], exec
	s_cselect_b32 s20, s43, s1
	s_cselect_b32 s34, s42, s0
	s_ashr_i32 s41, s40, 31
	s_lshl_b64 s[26:27], s[40:41], 19
	s_add_u32 s44, s36, s26
	s_addc_u32 s45, s37, s27
	s_and_b64 s[26:27], s[30:31], exec
	s_cselect_b32 s35, s45, s29
	s_cselect_b32 s36, s44, s28
	s_add_u32 s0, s0, 0x40080
	s_addc_u32 s1, s1, 0
	s_add_u32 s37, s28, 0x100
	v_mov_b32_e32 v0, 0
	s_addc_u32 s26, s29, 0
	s_mov_b32 s27, -2
	v_mov_b32_e32 v1, v0
	v_mov_b64_e32 v[2:3], 0
	v_mov_b64_e32 v[4:5], 0
	v_mov_b64_e32 v[6:7], 0
	v_mov_b64_e32 v[8:9], 0
	v_mov_b64_e32 v[10:11], 0
	v_mov_b64_e32 v[12:13], 0
	v_mov_b64_e32 v[14:15], 0
	v_mov_b64_e32 v[16:17], 0
	v_mov_b64_e32 v[18:19], 0
	v_mov_b64_e32 v[20:21], 0
	v_mov_b64_e32 v[22:23], 0
	v_mov_b64_e32 v[24:25], 0
	v_mov_b64_e32 v[26:27], 0
	v_mov_b64_e32 v[28:29], 0
	v_mov_b64_e32 v[30:31], 0
	v_mov_b64_e32 v[32:33], 0
	v_mov_b64_e32 v[34:35], 0
	v_mov_b64_e32 v[36:37], 0
	v_mov_b64_e32 v[38:39], 0
	v_mov_b64_e32 v[40:41], 0
	v_mov_b64_e32 v[42:43], 0
	v_mov_b64_e32 v[44:45], 0
	v_mov_b64_e32 v[46:47], 0
	v_mov_b64_e32 v[48:49], 0
	v_mov_b64_e32 v[50:51], 0
	v_mov_b64_e32 v[52:53], 0
	v_mov_b64_e32 v[54:55], 0
	v_mov_b64_e32 v[56:57], 0
	v_mov_b64_e32 v[58:59], 0
	v_mov_b64_e32 v[60:61], 0
	v_mov_b64_e32 v[62:63], 0
	v_mov_b64_e32 v[64:65], 0
	v_mov_b64_e32 v[66:67], 0
	v_mov_b64_e32 v[68:69], 0
	v_mov_b64_e32 v[70:71], 0
	v_mov_b64_e32 v[72:73], 0
	v_mov_b64_e32 v[74:75], 0
	v_mov_b64_e32 v[76:77], 0
	v_mov_b64_e32 v[78:79], 0
	v_mov_b64_e32 v[80:81], 0
	v_mov_b64_e32 v[82:83], 0
	v_mov_b64_e32 v[84:85], 0
	v_mov_b64_e32 v[86:87], 0
	v_mov_b64_e32 v[88:89], 0
	v_mov_b64_e32 v[90:91], 0
	v_mov_b64_e32 v[92:93], 0
	v_mov_b64_e32 v[94:95], 0
	v_mov_b64_e32 v[96:97], 0
	v_mov_b64_e32 v[98:99], 0
	v_mov_b64_e32 v[100:101], 0
	v_mov_b64_e32 v[102:103], 0
	v_mov_b64_e32 v[104:105], 0
	v_mov_b64_e32 v[106:107], 0
	v_mov_b64_e32 v[108:109], 0
	v_mov_b64_e32 v[110:111], 0
	v_mov_b64_e32 v[112:113], 0
	v_mov_b64_e32 v[114:115], 0
	v_mov_b64_e32 v[116:117], 0
	v_mov_b64_e32 v[118:119], 0
	v_mov_b64_e32 v[120:121], 0
	v_mov_b64_e32 v[122:123], 0
	v_mov_b64_e32 v[124:125], 0
	v_mov_b64_e32 v[126:127], 0
	s_nop 1
	v_add_u32_e32 v230, 0x10000, v143
